# sw_rows ph6 grouped prefetch + EpiRes prologue loads batched + attention QK wait fix
# speedup vs baseline: 1.0044x; 1.0044x over previous
.LBB0_475:
	s_sub_i32 s4, s3, 32
	s_lshr_b32 s4, s4, 3
	s_mul_i32 s4, s4, 9
	s_add_i32 s4, s4, 9
	s_cmp_lt_i32 s3, 32
	s_cselect_b32 s6, 0, s4
	v_readlane_b32 s76, v253, 33
	v_readlane_b32 s4, v252, 18
	v_readlane_b32 s77, v253, 34
	s_cselect_b32 s8, s76, s4
	v_readlane_b32 s4, v252, 19
	s_cselect_b32 s9, s77, s4
	s_add_i32 s4, s6, s16
	s_lshl_b32 s4, s4, 10
	s_ashr_i32 s5, s4, 31
	s_lshl_b64 s[4:5], s[4:5], 2
	s_add_u32 s4, s75, s4
	s_addc_u32 s5, s95, s5
	s_add_i32 s6, s92, s6
	s_lshl_b32 s6, s6, 10
	s_addk_i32 s6, 0x400
	s_ashr_i32 s7, s6, 31
	s_lshl_b64 s[6:7], s[6:7], 2
	s_add_u32 s6, s40, s6
	s_addc_u32 s7, s41, s7
	s_lshl_b32 s2, s2, 8
	v_mov_b32_e32 v140, v215
	v_mov_b32_e32 v141, v207
	s_or_b32 s2, s2, s68
	v_mov_b32_e32 v219, v218
	v_lshl_add_u32 v222, v141, 2, s2
	v_ashrrev_i32_e32 v223, 31, v222
	v_lshlrev_b64 v[194:195], 2, v[222:223]
	v_lshl_add_u64 v[134:135], s[4:5], 0, v[194:195]
	v_lshl_add_u64 v[136:137], s[56:57], 0, v[194:195]
	v_lshl_add_u64 v[138:139], s[6:7], 0, v[194:195]
	global_load_dwordx4 v[198:201], v[134:135], off
	global_load_dwordx4 v[230:233], v[134:135], off offset:64
	global_load_dwordx4 v[234:237], v[134:135], off offset:512
	global_load_dwordx4 v[238:241], v[134:135], off offset:576
	global_load_dwordx4 v[154:157], v[136:137], off
	global_load_dwordx4 v[158:161], v[138:139], off
	global_load_dwordx4 v[166:169], v[136:137], off offset:64
	global_load_dwordx4 v[178:181], v[138:139], off offset:64
	global_load_dwordx4 v[162:165], v[136:137], off offset:512
	global_load_dwordx4 v[174:177], v[138:139], off offset:512
	global_load_dwordx4 v[182:185], v[136:137], off offset:576
	global_load_dwordx4 v[186:189], v[138:139], off offset:576
	s_lshl_b32 s2, s3, 8
	v_readlane_b32 s78, v253, 35
	v_readlane_b32 s79, v253, 36
	v_readlane_b32 s80, v253, 37
	v_readlane_b32 s81, v253, 38
	v_readlane_b32 s82, v253, 39
	v_readlane_b32 s83, v253, 40
	s_add_i32 s2, s2, s67
	v_add_u32_e32 v224, s2, v140
	v_readlane_b32 s76, v252, 3
	s_and_b64 s[2:3], s[60:61], exec
	v_readlane_b32 s82, v252, 9
	v_readlane_b32 s83, v252, 10
	v_ashrrev_i32_e32 v225, 31, v224
	v_add_u32_e32 v246, 16, v224
	s_cselect_b32 s3, s9, s83
	s_cselect_b32 s2, s8, s82
	v_ashrrev_i32_e32 v247, 31, v246
	v_lshl_add_u64 v[244:245], s[2:3], 0, v[194:195]
	v_lshlrev_b64 v[248:249], 12, v[246:247]
	v_cmp_eq_u32_e64 s[36:37], 0, v141
	s_mov_b64 s[4:5], -1
	s_and_b64 vcc, exec, s[54:55]
	v_readlane_b32 s84, v253, 41
	v_readlane_b32 s85, v253, 42
	v_readlane_b32 s86, v253, 43
	v_readlane_b32 s87, v253, 44
	v_readlane_b32 s88, v253, 45
	v_readlane_b32 s89, v253, 46
	v_readlane_b32 s90, v253, 47
	v_readlane_b32 s91, v253, 48
	v_readlane_b32 s77, v252, 4
	v_readlane_b32 s78, v252, 5
	v_readlane_b32 s79, v252, 6
	v_readlane_b32 s80, v252, 7
	v_readlane_b32 s81, v252, 8
	v_lshlrev_b64 v[130:131], 12, v[224:225]
	v_lshl_add_u64 v[132:133], s[2:3], 0, v[130:131]
	v_lshl_add_u64 v[132:133], v[132:133], 0, v[194:195]
	v_lshl_add_u64 v[196:197], s[82:83], 0, v[130:131]
	v_lshl_add_u64 v[242:243], v[244:245], 0, v[248:249]
	global_load_dwordx4 v[190:193], v[132:133], off
	global_load_dwordx4 v[170:173], v[132:133], off offset:64
	global_load_dwordx4 v[150:153], v[132:133], off offset:512
	global_load_dwordx4 v[146:149], v[132:133], off offset:576
	global_load_dwordx4 v[142:145], v[242:243], off
	global_load_dwordx4 v[138:141], v[242:243], off offset:64
	global_load_dwordx4 v[134:137], v[242:243], off offset:512
	global_load_dwordx4 v[130:133], v[242:243], off offset:576
	v_lshl_add_u64 v[250:251], v[196:197], 0, v[194:195]
	s_waitcnt vmcnt(16)
	v_pk_mul_f32 v[226:227], v[218:219], v[240:241]
	v_pk_mul_f32 v[240:241], v[220:221], v[238:239]
	v_pk_mul_f32 v[238:239], v[220:221], v[234:235]
	v_pk_mul_f32 v[228:229], v[218:219], v[236:237]
	v_pk_mul_f32 v[236:237], v[220:221], v[230:231]
	v_pk_mul_f32 v[230:231], v[218:219], v[232:233]
	v_pk_mul_f32 v[234:235], v[220:221], v[198:199]
	v_pk_mul_f32 v[232:233], v[218:219], v[200:201]
	s_waitcnt vmcnt(7)
	v_pk_fma_f32 v[128:129], v[128:129], v[232:233], v[192:193]
	v_pk_fma_f32 v[126:127], v[126:127], v[234:235], v[190:191]
	s_waitcnt vmcnt(6)
	v_pk_fma_f32 v[198:199], v[122:123], v[236:237], v[170:171]
	s_waitcnt vmcnt(5)
	v_pk_fma_f32 v[194:195], v[118:119], v[238:239], v[150:151]
	s_waitcnt vmcnt(4)
	v_pk_fma_f32 v[190:191], v[114:115], v[240:241], v[146:147]
	global_store_dwordx4 v[250:251], v[126:129], off
	s_cbranch_vccz .LBB0_477
	v_pk_fma_f32 v[200:201], v[124:125], v[230:231], v[172:173]
	v_pk_fma_f32 v[196:197], v[120:121], v[228:229], v[152:153]
	v_pk_fma_f32 v[192:193], v[116:117], v[226:227], v[148:149]
	global_store_dwordx4 v[250:251], v[198:201], off offset:64
	global_store_dwordx4 v[250:251], v[194:197], off offset:512
	global_store_dwordx4 v[250:251], v[190:193], off offset:576
	s_mov_b64 s[4:5], 0

.LBB0_641:
	s_cmp_lg_u32 s2, 1
	s_cselect_b64 s[10:11], -1, 0
	s_or_b64 s[10:11], s[10:11], s[4:5]
	s_and_b64 vcc, exec, s[10:11]
	s_cbranch_vccnz .LBB0_640
	global_load_dwordx4 v[2:5], v[54:55], off
	global_load_dwordx4 v[6:9], v[54:55], off offset:16
	global_load_dwordx4 v[10:13], v[54:55], off offset:32
	global_load_dwordx4 v[14:17], v[54:55], off offset:48
	global_load_dwordx4 v[18:21], v[56:57], off
	global_load_dwordx4 v[22:25], v[56:57], off offset:16
	global_load_dwordx4 v[26:29], v[56:57], off offset:32
	global_load_dwordx4 v[30:33], v[56:57], off offset:48
	global_load_dwordx4 v[34:37], v[52:53], off
	global_load_dwordx4 v[38:41], v[52:53], off offset:16
	global_load_dwordx4 v[42:45], v[52:53], off offset:32
	global_load_dwordx4 v[46:49], v[52:53], off offset:48
	v_mov_b64_e32 v[60:61], v[58:59]
	s_mov_b32 s3, s42
	v_lshl_add_u64 v[232:233], v[60:61], 0, s[8:9]
	v_lshl_add_u64 v[234:235], v[232:233], 0, s[8:9]
	global_load_dwordx4 v[168:171], v[60:61], off offset:16
	global_load_dwordx4 v[172:175], v[60:61], off
	global_load_dwordx4 v[176:179], v[232:233], off offset:16
	global_load_dwordx4 v[180:183], v[232:233], off
	global_load_dwordx4 v[184:187], v[234:235], off offset:16
	global_load_dwordx4 v[188:191], v[234:235], off
	v_lshl_add_u64 v[60:61], v[234:235], 0, s[8:9]
	s_branch .Lsw6_top
.LBB0_643:
	s_or_b64 exec, exec, s[10:11]
	s_add_i32 s3, s3, s44
	s_cmpk_lt_i32 s3, 0x1600
	s_cbranch_scc0 .LBB0_640
	s_add_i32 s32, s32, -1
	s_cmp_lg_u32 s32, 0
	s_cbranch_scc0 .Lsw6_top
	v_mov_b32_e32 v68, v216
	v_mov_b32_e32 v69, v217
	v_mov_b32_e32 v70, v218
	v_mov_b32_e32 v71, v219
	v_mov_b32_e32 v72, v220
	v_mov_b32_e32 v73, v221
	v_mov_b32_e32 v74, v222
	v_mov_b32_e32 v75, v223
	v_mov_b32_e32 v216, v224
	v_mov_b32_e32 v217, v225
	v_mov_b32_e32 v218, v226
	v_mov_b32_e32 v219, v227
	v_mov_b32_e32 v220, v228
	v_mov_b32_e32 v221, v229
	v_mov_b32_e32 v222, v230
	v_mov_b32_e32 v223, v231
	s_branch .LBB0_644
.Lsw6_top:
	s_waitcnt vmcnt(0)
	v_mov_b32_e32 v68, v168
	v_mov_b32_e32 v69, v169
	v_mov_b32_e32 v70, v170
	v_mov_b32_e32 v71, v171
	v_mov_b32_e32 v72, v172
	v_mov_b32_e32 v73, v173
	v_mov_b32_e32 v74, v174
	v_mov_b32_e32 v75, v175
	v_mov_b32_e32 v216, v176
	v_mov_b32_e32 v217, v177
	v_mov_b32_e32 v218, v178
	v_mov_b32_e32 v219, v179
	v_mov_b32_e32 v220, v180
	v_mov_b32_e32 v221, v181
	v_mov_b32_e32 v222, v182
	v_mov_b32_e32 v223, v183
	v_mov_b32_e32 v224, v184
	v_mov_b32_e32 v225, v185
	v_mov_b32_e32 v226, v186
	v_mov_b32_e32 v227, v187
	v_mov_b32_e32 v228, v188
	v_mov_b32_e32 v229, v189
	v_mov_b32_e32 v230, v190
	v_mov_b32_e32 v231, v191
	v_lshl_add_u64 v[232:233], v[60:61], 0, s[8:9]
	v_lshl_add_u64 v[234:235], v[232:233], 0, s[8:9]
	global_load_dwordx4 v[168:171], v[60:61], off offset:16
	global_load_dwordx4 v[172:175], v[60:61], off
	global_load_dwordx4 v[176:179], v[232:233], off offset:16
	global_load_dwordx4 v[180:183], v[232:233], off
	global_load_dwordx4 v[184:187], v[234:235], off offset:16
	global_load_dwordx4 v[188:191], v[234:235], off
	v_lshl_add_u64 v[60:61], v[234:235], 0, s[8:9]
	s_mov_b32 s32, 3
.LBB0_644:
	v_lshlrev_b32_e32 v51, 16, v68
	v_and_b32_e32 v77, 0xffff0000, v72
	v_and_b32_e32 v79, 0xffff0000, v73
	v_lshlrev_b32_e32 v76, 16, v72
	v_and_b32_e32 v66, 0xffff0000, v68
	v_lshlrev_b32_e32 v78, 16, v73
	v_lshlrev_b32_e32 v64, 16, v69
	v_and_b32_e32 v68, 0xffff0000, v69
	v_lshlrev_b32_e32 v65, 16, v71
	v_and_b32_e32 v69, 0xffff0000, v71
	v_mul_f32_e32 v71, v35, v77
	v_mul_f32_e32 v72, v37, v79
	v_and_b32_e32 v81, 0xffff0000, v74
	v_lshlrev_b32_e32 v62, 16, v70
	v_and_b32_e32 v67, 0xffff0000, v70
	v_lshlrev_b32_e32 v70, 16, v75
	v_and_b32_e32 v75, 0xffff0000, v75
	v_fmac_f32_e32 v71, v34, v76
	v_fmac_f32_e32 v72, v36, v78
	v_lshlrev_b32_e32 v80, 16, v74
	v_add_f32_e32 v71, v71, v72
	v_mul_f32_e32 v72, v39, v81
	v_mul_f32_e32 v73, v41, v75
	v_fmac_f32_e32 v72, v38, v80
	v_fmac_f32_e32 v73, v40, v70
	v_add_f32_e32 v71, 0, v71
	v_add_f32_e32 v72, v72, v73
	v_add_f32_e32 v71, v72, v71
	v_mul_f32_e32 v72, v43, v66
	v_mul_f32_e32 v73, v45, v68
	v_fmac_f32_e32 v72, v42, v51
	v_fmac_f32_e32 v73, v44, v64
	v_add_f32_e32 v72, v72, v73
	v_add_f32_e32 v71, v72, v71
	v_mul_f32_e32 v72, v47, v67
	v_mul_f32_e32 v73, v49, v69
	v_fmac_f32_e32 v72, v46, v62
	v_fmac_f32_e32 v73, v48, v65
	v_add_f32_e32 v72, v72, v73
	v_mul_f32_e32 v73, v19, v77
	v_mul_f32_e32 v74, v21, v79
	v_fmac_f32_e32 v73, v18, v76
	v_fmac_f32_e32 v74, v20, v78
	v_add_f32_e32 v73, v73, v74
	v_mul_f32_e32 v74, v23, v81
	v_mul_f32_e32 v82, v25, v75
	v_fmac_f32_e32 v74, v22, v80
	v_fmac_f32_e32 v82, v24, v70
	v_add_f32_e32 v73, 0, v73
	v_add_f32_e32 v74, v74, v82
	v_mul_f32_e32 v77, v3, v77
	v_add_f32_e32 v73, v74, v73
	v_mul_f32_e32 v74, v27, v66
	v_mul_f32_e32 v82, v29, v68
	v_fmac_f32_e32 v77, v2, v76
	v_mul_f32_e32 v76, v5, v79
	v_fmac_f32_e32 v74, v26, v51
	v_fmac_f32_e32 v82, v28, v64
	v_fmac_f32_e32 v76, v4, v78
	v_mul_f32_e32 v66, v11, v66
	v_add_f32_e32 v74, v74, v82
	v_add_f32_e32 v76, v77, v76
	v_mul_f32_e32 v77, v7, v81
	v_mul_f32_e32 v75, v9, v75
	v_fmac_f32_e32 v66, v10, v51
	v_mul_f32_e32 v51, v13, v68
	v_add_f32_e32 v73, v74, v73
	v_mul_f32_e32 v74, v31, v67
	v_fmac_f32_e32 v77, v6, v80
	v_fmac_f32_e32 v75, v8, v70
	v_fmac_f32_e32 v51, v12, v64
	v_mul_f32_e32 v64, v15, v67
	v_fmac_f32_e32 v74, v30, v62
	v_mul_f32_e32 v82, v33, v69
	v_add_f32_e32 v76, 0, v76
	v_add_f32_e32 v70, v77, v75
	v_fmac_f32_e32 v64, v14, v62
	v_mul_f32_e32 v62, v17, v69
	v_fmac_f32_e32 v82, v32, v65
	v_add_f32_e32 v70, v70, v76
	v_add_f32_e32 v51, v66, v51
	v_fmac_f32_e32 v62, v16, v65
	v_add_f32_e32 v74, v74, v82
	v_add_f32_e32 v51, v51, v70
	v_add_f32_e32 v62, v64, v62
	v_add_f32_e32 v71, v72, v71
	v_add_f32_e32 v73, v74, v73
	v_add_f32_e32 v51, v62, v51
	v_add_f32_dpp v71, v71, v71 quad_perm:[1,0,3,2] row_mask:0xf bank_mask:0xf bound_ctrl:1
	v_add_f32_dpp v73, v73, v73 quad_perm:[1,0,3,2] row_mask:0xf bank_mask:0xf bound_ctrl:1
	v_add_f32_dpp v51, v51, v51 quad_perm:[1,0,3,2] row_mask:0xf bank_mask:0xf bound_ctrl:1
	v_add_f32_dpp v71, v71, v71 quad_perm:[2,3,0,1] row_mask:0xf bank_mask:0xf bound_ctrl:1
	v_add_f32_dpp v73, v73, v73 quad_perm:[2,3,0,1] row_mask:0xf bank_mask:0xf bound_ctrl:1
	v_add_f32_dpp v51, v51, v51 quad_perm:[2,3,0,1] row_mask:0xf bank_mask:0xf bound_ctrl:1
	v_add_f32_dpp v71, v71, v71 row_ror:4 row_mask:0xf bank_mask:0xf bound_ctrl:1
	v_add_f32_dpp v73, v73, v73 row_ror:4 row_mask:0xf bank_mask:0xf bound_ctrl:1
	v_add_f32_dpp v51, v51, v51 row_ror:4 row_mask:0xf bank_mask:0xf bound_ctrl:1
	v_add_f32_dpp v71, v71, v71 row_ror:8 row_mask:0xf bank_mask:0xf bound_ctrl:1
	v_add_f32_dpp v73, v73, v73 row_ror:8 row_mask:0xf bank_mask:0xf bound_ctrl:1
	v_add_f32_dpp v51, v51, v51 row_ror:8 row_mask:0xf bank_mask:0xf bound_ctrl:1
	v_mov_b32_e32 v72, v71
	v_mov_b32_e32 v74, v73
	v_mov_b32_e32 v62, v51
	v_permlane16_swap_b32_e32 v71, v72
	v_permlane16_swap_b32_e32 v73, v74
	v_permlane16_swap_b32_e32 v51, v62
	v_add_f32_e32 v71, v71, v72
	v_add_f32_e32 v73, v73, v74
	v_add_f32_e32 v51, v51, v62
	v_mov_b32_e32 v72, v71
	v_mov_b32_e32 v74, v73
	v_mov_b32_e32 v62, v51
	v_permlane32_swap_b32_e32 v71, v72
	v_permlane32_swap_b32_e32 v73, v74
	v_permlane32_swap_b32_e32 v51, v62
	s_and_saveexec_b64 s[10:11], s[34:35]
	s_cbranch_execz .LBB0_643
	v_add_f32_e32 v51, v51, v62
	v_add_f32_e32 v62, v73, v74
	v_add_f32_e32 v64, v71, v72
	v_cndmask_b32_e64 v51, v51, v62, s[38:39]
	v_cndmask_b32_e64 v51, v51, v64, s[36:37]
	v_add_u32_e32 v64, s3, v0
	v_ashrrev_i32_e32 v65, 31, v64
	v_lshl_add_u64 v[64:65], v[64:65], 2, s[6:7]
	global_store_dword v[64:65], v51, off
	s_branch .LBB0_643

.LBB0_701:
	s_or_b64 exec, exec, s[0:1]
	s_cmp_lt_i32 s2, 1
	s_waitcnt lgkmcnt(0)
	s_barrier
	s_cbranch_scc1 .LBB0_810
	v_or_b32_e32 v0, s23, v91
	v_max_i32_e32 v0, 8, v0
	v_add_u32_e32 v0, -8, v0
	v_writelane_b32 v255, s24, 34
	v_min_u32_e32 v0, 48, v0
	v_cmp_ge_u32_e64 s[0:1], v94, v0
	v_writelane_b32 v255, s25, 35
	s_waitcnt vmcnt(6)
	v_add_u32_e32 v2, 16, v0
	v_writelane_b32 v255, s0, 0
	v_cmp_lt_u32_e32 vcc, v94, v0
	s_mov_b32 s27, s31
	v_writelane_b32 v255, s1, 1
	v_cmp_ge_u32_e64 s[0:1], v107, v0
	s_add_i32 s33, s28, 8
	s_lshl_b64 s[24:25], s[26:27], 7
	v_writelane_b32 v255, s0, 2
	v_cmp_ge_u32_e64 s[44:45], v108, v0
	v_cmp_ge_u32_e64 s[46:47], v109, v0
	v_writelane_b32 v255, s1, 3
	v_cmp_ge_u32_e64 s[0:1], v114, v0
	s_and_b64 s[10:11], s[0:1], vcc
	v_cmp_ge_u32_e32 vcc, v115, v0
	v_cmp_lt_u32_e64 s[0:1], v115, v2
	s_and_b64 s[12:13], vcc, s[0:1]
	v_cmp_ge_u32_e32 vcc, v116, v0
	v_cmp_lt_u32_e64 s[0:1], v116, v2
	s_and_b64 s[14:15], vcc, s[0:1]
	v_cmp_ge_u32_e32 vcc, v117, v0
	v_cmp_lt_u32_e64 s[0:1], v117, v2
	s_and_b64 s[16:17], vcc, s[0:1]
	v_cmp_ge_u32_e32 vcc, v118, v0
	v_cmp_lt_u32_e64 s[0:1], v118, v2
	s_and_b64 s[18:19], vcc, s[0:1]
	v_cmp_ge_u32_e32 vcc, v119, v0
	v_cmp_lt_u32_e64 s[0:1], v119, v2
	s_and_b64 s[72:73], vcc, s[0:1]
	v_cmp_ge_u32_e32 vcc, v120, v0
	v_cmp_lt_u32_e64 s[0:1], v120, v2
	s_and_b64 s[76:77], vcc, s[0:1]
	v_cmp_ge_u32_e32 vcc, v121, v0
	v_cmp_lt_u32_e64 s[0:1], v121, v2
	s_and_b64 s[78:79], vcc, s[0:1]
	v_cmp_ge_u32_e32 vcc, v122, v0
	v_cmp_lt_u32_e64 s[0:1], v122, v2
	s_and_b64 s[80:81], vcc, s[0:1]
	v_cmp_ge_u32_e32 vcc, v123, v0
	v_cmp_lt_u32_e64 s[0:1], v123, v2
	s_and_b64 s[82:83], vcc, s[0:1]
	v_cmp_ge_u32_e32 vcc, v124, v0
	v_cmp_lt_u32_e64 s[0:1], v124, v2
	s_and_b64 s[84:85], vcc, s[0:1]
	v_cmp_ge_u32_e32 vcc, v125, v0
	v_cmp_lt_u32_e64 s[0:1], v125, v2
	s_and_b64 s[86:87], vcc, s[0:1]
	v_cmp_ge_u32_e32 vcc, v126, v0
	v_cmp_lt_u32_e64 s[0:1], v126, v2
	s_and_b64 s[88:89], vcc, s[0:1]
	v_cmp_ge_u32_e32 vcc, v127, v0
	v_cmp_lt_u32_e64 s[0:1], v127, v2
	s_and_b64 s[90:91], vcc, s[0:1]
	v_cmp_ge_u32_e32 vcc, v128, v0
	v_cmp_lt_u32_e64 s[0:1], v128, v2
	s_and_b64 s[20:21], vcc, s[0:1]
	v_cmp_ge_u32_e32 vcc, v129, v0
	v_cmp_lt_u32_e64 s[0:1], v129, v2
	s_and_b64 s[0:1], vcc, s[0:1]
	s_add_u32 s24, s36, s24
	s_addc_u32 s25, s37, s25
	s_add_u32 s34, s24, 0xfffffd00
	v_cmp_ge_u32_e64 s[48:49], v110, v0
	v_cmp_ge_u32_e64 s[50:51], v111, v0
	v_cmp_ge_u32_e64 s[52:53], v112, v0
	v_cmp_ge_u32_e64 s[54:55], v113, v0
	s_addc_u32 s35, s25, -1
	s_lshl_b64 s[24:25], s[26:27], 13
	s_mul_i32 s27, s26, 0x7c
	v_add_lshl_u32 v0, v91, s23, 2
	v_sub_u32_e32 v0, s27, v0
	s_mulk_i32 s22, 0x7c
	s_add_u32 s24, s94, s24
	v_subrev_u32_e32 v0, s22, v0
	v_mov_b32_e32 v14, v1
	v_mov_b32_e32 v15, v1
	v_cmp_lt_u32_e64 s[56:57], v130, v2
	v_cmp_lt_u32_e64 s[58:59], v131, v2
	v_cmp_lt_u32_e64 s[60:61], v132, v2
	v_cmp_lt_u32_e64 s[62:63], v133, v2
	v_cmp_lt_u32_e64 s[64:65], v134, v2
	v_cmp_lt_u32_e64 s[66:67], v135, v2
	v_cmp_lt_u32_e64 s[68:69], v136, v2
	v_cmp_lt_u32_e64 s[70:71], v137, v2
	s_addc_u32 s25, s95, s25
	v_add_u32_e32 v99, v138, v0
	v_mov_b32_e32 v0, v1
	v_mov_b32_e32 v2, v1
	v_mov_b32_e32 v3, v1
	v_mov_b32_e32 v4, v1
	v_mov_b32_e32 v5, v1
	v_mov_b32_e32 v6, v1
	v_mov_b32_e32 v7, v1
	v_mov_b32_e32 v8, v1
	v_mov_b32_e32 v9, v1
	v_mov_b32_e32 v10, v1
	v_mov_b32_e32 v11, v1
	v_mov_b32_e32 v12, v1
	v_mov_b32_e32 v13, v1
	v_mov_b64_e32 v[32:33], v[14:15]
	s_add_u32 s24, s24, 0xffff4000
	v_mov_b64_e32 v[30:31], v[12:13]
	v_mov_b64_e32 v[28:29], v[10:11]
	v_mov_b64_e32 v[26:27], v[8:9]
	v_mov_b64_e32 v[24:25], v[6:7]
	v_mov_b64_e32 v[22:23], v[4:5]
	v_mov_b64_e32 v[20:21], v[2:3]
	v_mov_b64_e32 v[18:19], v[0:1]
	v_mov_b64_e32 v[16:17], v[14:15]
	s_addc_u32 s25, s25, -1
	s_add_i32 s29, s26, -8
	s_mov_b32 s41, 0
	v_mov_b32_e32 v97, 0
	v_mov_b32_e32 v101, 0xf149f2ca
	s_movk_i32 s26, 0xf880
	v_mov_b64_e32 v[14:15], v[12:13]
	v_mov_b64_e32 v[12:13], v[10:11]
	v_mov_b64_e32 v[10:11], v[8:9]
	v_mov_b64_e32 v[8:9], v[6:7]
	v_mov_b64_e32 v[6:7], v[4:5]
	v_mov_b64_e32 v[4:5], v[2:3]
	v_mov_b64_e32 v[2:3], v[0:1]
	s_waitcnt vmcnt(0)
	s_add_i32 s40, s41, 1
	s_cmp_ge_i32 s40, s2
	s_cbranch_scc1 .LBB0_708

.LBB0_716:
	s_cmp_lt_u32 s41, 8
	s_cselect_b64 s[22:23], -1, 0
	s_or_b64 s[22:23], s[4:5], s[22:23]
	s_add_i32 s27, s29, s41
	s_cmp_ge_i32 s27, s28
	s_cselect_b64 s[42:43], -1, 0
	s_cmp_lt_i32 s27, s33
	s_cselect_b64 s[74:75], -1, 0
	s_and_b64 s[42:43], s[42:43], s[74:75]
	s_or_b64 s[42:43], s[22:23], s[42:43]
	s_andn2_b64 vcc, exec, s[42:43]
	s_cbranch_vccnz .LBB0_798
	s_add_i32 s27, s26, 0x780
	s_and_b32 s27, s27, 64
	s_mulk_i32 s27, 0x90
	v_add_u32_e32 v0, s27, v106
	ds_read_b128 v[34:37], v0
	ds_read_b128 v[140:143], v0 offset:4640
	s_xor_b64 s[22:23], s[22:23], -1
	s_andn2_b64 vcc, exec, s[22:23]
	s_waitcnt lgkmcnt(1)
	v_mfma_f32_32x32x16_bf16 v[50:65], v[34:37], v[66:69], 0
	ds_read_b128 v[34:37], v0 offset:32
	s_waitcnt lgkmcnt(0)
	v_mfma_f32_32x32x16_bf16 v[50:65], v[34:37], v[70:73], v[50:65]
	ds_read_b128 v[34:37], v0 offset:64
	s_waitcnt lgkmcnt(0)
	v_mfma_f32_32x32x16_bf16 v[50:65], v[34:37], v[74:77], v[50:65]
	ds_read_b128 v[34:37], v0 offset:96
	s_waitcnt lgkmcnt(0)
	v_mfma_f32_32x32x16_bf16 v[50:65], v[34:37], v[78:81], v[50:65]
	ds_read_b128 v[34:37], v0 offset:4608
	s_waitcnt lgkmcnt(0)
	v_mfma_f32_32x32x16_bf16 v[34:49], v[34:37], v[66:69], 0
	v_mfma_f32_32x32x16_bf16 v[34:49], v[140:143], v[70:73], v[34:49]
	ds_read_b128 v[140:143], v0 offset:4672
	s_waitcnt lgkmcnt(0)
	v_mfma_f32_32x32x16_bf16 v[34:49], v[140:143], v[74:77], v[34:49]
	ds_read_b128 v[140:143], v0 offset:4704
	s_waitcnt lgkmcnt(0)
	v_mfma_f32_32x32x16_bf16 v[34:49], v[140:143], v[78:81], v[34:49]
	s_cbranch_vccnz .LBB0_794
	v_mov_b32_e32 v139, 0xf149f2ca
	v_mov_b32_e32 v140, 0xf149f2ca
	s_mov_b64 s[22:23], exec
	v_readlane_b32 s42, v255, 0
	v_readlane_b32 s43, v255, 1
	s_and_b64 s[42:43], s[22:23], s[42:43]
	s_mov_b64 exec, s[42:43]
	s_cbranch_execz .LBB0_720
	ds_read_b32 v140, v99
	s_waitcnt lgkmcnt(0)
	v_add_f32_e32 v140, v50, v140
